# GEMM phase prologue: all 14 stage loads in flight before the first wait (vmcnt(8)) instead of 8 + wait + barrier + 6
# speedup vs baseline: 1.0008x; 1.0008x over previous
.Lold_0:
	s_add_u32 s6, s30, 0x160000
	s_addc_u32 s7, s31, 0
	s_add_u32 s49, s30, 0x13900000
	s_addc_u32 s56, s31, 0
	s_lshl_b32 s10, s10, 5
	s_and_b32 s16, s10, 0x60
	s_mov_b64 s[10:11], 0x80
	s_add_i32 m0, s23, 0x18000
	v_lshl_add_u64 v[6:7], v[6:7], 0, s[10:11]
	s_lshl_b32 s13, s3, 13
	s_lshl_b32 s17, s16, 7
	global_load_lds_dwordx4 v[6:7], off
	v_lshl_add_u64 v[4:5], v[4:5], 0, s[10:11]
	s_add_i32 m0, s23, 0x1a000
	s_add_i32 s57, s23, 0x8000
	s_add_i32 s58, s23, 0xa000
	global_load_lds_dwordx4 v[4:5], off
	v_lshl_add_u64 v[0:1], v[0:1], 0, s[10:11]
	s_mov_b32 m0, s57
	s_add_u32 s14, s26, 0x40080
	global_load_lds_dwordx4 v[0:1], off
	v_lshl_add_u64 v[0:1], v[2:3], 0, s[10:11]
	s_mov_b32 m0, s58
	s_addc_u32 s15, s27, 0
	global_load_lds_dwordx4 v[0:1], off
	s_add_i32 m0, s23, 0x1c000
	v_lshl_add_u64 v[0:1], s[14:15], 0, v[146:147]
	global_load_lds_dwordx4 v[0:1], off
	v_lshl_add_u64 v[0:1], s[14:15], 0, v[150:151]
	s_add_i32 m0, s23, 0x1e000
	v_and_b32_e32 v2, 15, v8
	global_load_lds_dwordx4 v[0:1], off
	v_bfe_u32 v1, v8, 4, 2
	v_lshlrev_b32_e32 v0, 3, v1
	v_lshlrev_b32_e32 v1, 4, v1
	v_lshl_or_b32 v168, s3, 6, v2
	v_lshl_or_b32 v1, v2, 6, v1
	v_lshlrev_b32_e32 v2, 2, v8
	v_and_b32_e32 v2, 32, v2
	v_bitop3_b32 v3, v1, s13, v2 bitop3:0xde
	v_bitop3_b32 v169, v1, s17, v2 bitop3:0xde
	v_lshlrev_b32_e32 v1, 14, v9
	v_and_b32_e32 v1, 0xffff8000, v1
	v_lshl_add_u32 v1, v10, 11, v1
	v_and_b32_e32 v2, 1, v9
	v_lshl_or_b32 v1, v2, 6, v1
	v_lshl_add_u32 v152, v11, 1, v1
	v_lshlrev_b32_e32 v1, 14, v12
	v_and_b32_e32 v1, 0xffff8000, v1
	s_waitcnt vmcnt(8)
	s_barrier
	s_waitcnt vmcnt(6)
	s_cmpk_lt_u32 s12, 0x100
	v_lshl_add_u32 v1, v13, 11, v1
	v_and_b32_e32 v2, 1, v12
	s_cselect_b64 s[12:13], -1, 0
	v_lshl_or_b32 v1, v2, 6, v1
	s_add_i32 s60, 0, 0x10000
	s_add_i32 s61, 0, 0x14000
	s_sext_i32_i16 s64, s2
	s_ashr_i32 s59, s9, 31
	v_or_b32_e32 v170, s16, v0
	v_mov_b32_e32 v153, v147
	v_lshl_add_u32 v154, v14, 1, v1
	v_mov_b32_e32 v155, v147
	v_mov_b64_e32 v[156:157], 0x5ac
	v_mov_b64_e32 v[158:159], 0x5ab
	v_add_u32_e32 v171, s60, v169
	v_add_u32_e32 v172, s61, v169
	v_add_u32_e32 v173, 0, v3
	s_movk_i32 s62, 0x1600
	s_lshl_b32 s63, s16, 2
	v_lshlrev_b32_e32 v174, 2, v0
	v_mov_b32_e32 v175, 0x358637bd
	s_barrier
	s_branch .LBB0_213

.Lold_1:
	s_add_u32 s47, s30, 0x2000
	s_addc_u32 s48, s31, 0
	s_add_u32 s49, s30, 0x1c6000
	s_addc_u32 s54, s31, 0
	s_add_u32 s12, s30, 0x170800
	s_addc_u32 s13, s31, 0
	s_lshl_b32 s2, s2, 5
	s_mov_b64 s[16:17], 0x80
	s_and_b32 s26, s2, 0x60
	s_add_i32 m0, s40, 0x18000
	v_lshl_add_u64 v[6:7], v[6:7], 0, s[16:17]
	s_lshl_b32 s5, s0, 13
	s_lshl_b32 s18, s26, 7
	global_load_lds_dwordx4 v[6:7], off
	v_lshl_add_u64 v[4:5], v[4:5], 0, s[16:17]
	s_add_i32 m0, s40, 0x1a000
	s_add_i32 s55, s40, 0x8000
	s_add_i32 s56, s40, 0xa000
	global_load_lds_dwordx4 v[4:5], off
	v_lshl_add_u64 v[0:1], v[0:1], 0, s[16:17]
	s_mov_b32 m0, s55
	s_add_u32 s2, s24, 0xb0080
	global_load_lds_dwordx4 v[0:1], off
	v_lshl_add_u64 v[0:1], v[2:3], 0, s[16:17]
	s_mov_b32 m0, s56
	s_addc_u32 s3, s25, 0
	global_load_lds_dwordx4 v[0:1], off
	s_add_i32 m0, s40, 0x1c000
	v_lshl_add_u64 v[0:1], s[2:3], 0, v[162:163]
	global_load_lds_dwordx4 v[0:1], off
	v_lshl_add_u64 v[0:1], s[2:3], 0, v[166:167]
	s_add_i32 m0, s40, 0x1e000
	s_cmpk_lt_u32 s4, 0x100
	global_load_lds_dwordx4 v[0:1], off
	v_bfe_u32 v0, v8, 4, 2
	v_and_b32_e32 v1, 15, v8
	v_lshlrev_b32_e32 v2, 4, v0
	v_lshl_or_b32 v177, s0, 6, v1
	v_lshl_or_b32 v1, v1, 6, v2
	v_lshlrev_b32_e32 v2, 2, v8
	v_and_b32_e32 v2, 32, v2
	v_bitop3_b32 v3, v1, s5, v2 bitop3:0xde
	v_bitop3_b32 v206, v1, s18, v2 bitop3:0xde
	v_cmp_eq_u32_e64 s[2:3], 0, v0
	v_lshl_or_b32 v207, v0, 3, s26
	v_lshrrev_b32_e32 v1, 1, v9
	v_mul_lo_u32 v0, v11, s1
	s_mov_b32 s0, 0xb000
	v_mad_u64_u32 v[0:1], s[4:5], v1, s0, v[0:1]
	v_or_b32_e32 v0, v0, v10
	s_mov_b64 s[20:21], 0xb0080
	v_add_lshl_u32 v0, v0, v12, 1
	v_mov_b32_e32 v1, v163
	v_lshl_add_u64 v[168:169], v[0:1], 0, s[20:21]
	v_lshrrev_b32_e32 v1, 1, v13
	v_mul_lo_u32 v0, v14, s1
	v_mad_u64_u32 v[0:1], s[0:1], v1, s0, v[0:1]
	v_or_b32_e32 v0, v0, v15
	s_waitcnt vmcnt(8)
	s_barrier
	s_waitcnt vmcnt(6)
	v_add_lshl_u32 v0, v0, v16, 1
	v_mov_b32_e32 v1, v163
	s_cselect_b64 s[18:19], -1, 0
	v_lshl_add_u64 v[170:171], v[0:1], 0, s[20:21]
	s_add_i32 s59, 0, 0x10000
	s_add_i32 s60, 0, 0x14000
	v_mbcnt_lo_u32_b32 v0, -1, 0
	s_ashr_i32 s57, s9, 31
	s_ashr_i32 s58, s8, 31
	v_mov_b64_e32 v[172:173], 0x100
	v_mov_b64_e32 v[174:175], 0xff
	v_add_u32_e32 v208, s59, v206
	v_add_u32_e32 v209, s60, v206
	v_add_u32_e32 v210, 0, v3
	v_mbcnt_hi_u32_b32 v211, -1, v0
	s_barrier
	s_branch .LBB0_330

.Lold_2:
	s_add_u32 s14, s30, 0x170800
	s_addc_u32 s15, s31, 0
	s_add_u32 s57, s30, 0x13910800
	s_addc_u32 s58, s31, 0
	s_lshl_b32 s4, s4, 5
	s_and_b32 s18, s4, 0x60
	s_mov_b64 s[4:5], 0x80
	s_add_i32 m0, s35, 0x18000
	v_lshl_add_u64 v[6:7], v[6:7], 0, s[4:5]
	s_lshl_b32 s11, s10, 13
	s_lshl_b32 s19, s18, 7
	global_load_lds_dwordx4 v[6:7], off
	v_lshl_add_u64 v[2:3], v[2:3], 0, s[4:5]
	s_add_i32 m0, s35, 0x1a000
	s_add_i32 s59, s35, 0x8000
	s_add_i32 s60, s35, 0xa000
	global_load_lds_dwordx4 v[2:3], off
	v_lshl_add_u64 v[0:1], v[0:1], 0, s[4:5]
	s_mov_b32 m0, s59
	s_add_u32 s16, s44, 0x40080
	global_load_lds_dwordx4 v[0:1], off
	v_lshl_add_u64 v[0:1], v[4:5], 0, s[4:5]
	s_mov_b32 m0, s60
	s_addc_u32 s17, s45, 0
	global_load_lds_dwordx4 v[0:1], off
	s_add_i32 m0, s35, 0x1c000
	v_lshl_add_u64 v[0:1], s[16:17], 0, v[146:147]
	global_load_lds_dwordx4 v[0:1], off
	v_lshl_add_u64 v[0:1], s[16:17], 0, v[150:151]
	s_add_i32 m0, s35, 0x1e000
	v_and_b32_e32 v2, 15, v8
	global_load_lds_dwordx4 v[0:1], off
	v_bfe_u32 v1, v8, 4, 2
	v_lshlrev_b32_e32 v0, 3, v1
	v_lshlrev_b32_e32 v1, 4, v1
	v_lshl_or_b32 v164, s10, 6, v2
	v_lshl_or_b32 v1, v2, 6, v1
	v_lshlrev_b32_e32 v2, 2, v8
	v_and_b32_e32 v2, 32, v2
	v_bitop3_b32 v3, v1, s11, v2 bitop3:0xde
	v_bitop3_b32 v165, v1, s19, v2 bitop3:0xde
	v_lshlrev_b32_e32 v1, 14, v9
	v_and_b32_e32 v1, 0xffff8000, v1
	v_lshl_add_u32 v1, v10, 11, v1
	v_and_b32_e32 v2, 1, v9
	v_lshl_or_b32 v1, v2, 6, v1
	v_lshl_add_u32 v152, v11, 1, v1
	v_lshlrev_b32_e32 v1, 14, v12
	v_and_b32_e32 v1, 0xffff8000, v1
	s_waitcnt vmcnt(8)
	s_barrier
	s_waitcnt vmcnt(6)
	s_cmpk_lt_u32 s3, 0x100
	v_lshl_add_u32 v1, v13, 11, v1
	v_and_b32_e32 v2, 1, v12
	s_cselect_b64 s[10:11], -1, 0
	v_lshl_or_b32 v1, v2, 6, v1
	s_add_i32 s62, 0, 0x10000
	s_add_i32 s63, 0, 0x14000
	s_sext_i32_i8 s68, s2
	v_or_b32_e32 v166, s18, v0
	s_ashr_i32 s61, s9, 31
	v_mov_b32_e32 v153, v147
	v_lshl_add_u32 v154, v14, 1, v1
	v_mov_b32_e32 v155, v147
	v_mov_b64_e32 v[156:157], 0x100
	v_mov_b64_e32 v[158:159], 0xff
	v_add_u32_e32 v167, s62, v165
	v_add_u32_e32 v168, s63, v165
	v_add_u32_e32 v169, 0, v3
	s_lshl_b32 s64, s18, 2
	v_lshlrev_b32_e32 v170, 2, v0
	v_mov_b32_e32 v171, 0x358637bd
	s_mov_b32 s65, 0x48000
	s_mov_b64 s[16:17], 0x50000
	s_mov_b32 s66, 0x50000
	s_mov_b64 s[18:19], 0x58000
	s_mov_b32 s67, 0x58000
	s_barrier
	s_branch .LBB0_457

.Lold_3:
	s_add_u32 s58, s30, 0x5000
	s_addc_u32 s59, s31, 0
	s_add_u32 s60, s30, 0x1c9000
	s_addc_u32 s61, s31, 0
	s_lshl_b32 s3, s3, 5
	s_mov_b64 s[12:13], 0x80
	s_and_b32 s16, s3, 0x60
	s_add_i32 m0, s27, 0x18000
	v_lshl_add_u64 v[6:7], v[6:7], 0, s[12:13]
	s_lshl_b32 s15, s2, 13
	s_lshl_b32 s3, s16, 7
	global_load_lds_dwordx4 v[6:7], off
	v_lshl_add_u64 v[4:5], v[4:5], 0, s[12:13]
	s_add_i32 m0, s27, 0x1a000
	s_add_i32 s62, s27, 0x8000
	s_add_i32 s63, s27, 0xa000
	global_load_lds_dwordx4 v[4:5], off
	v_lshl_add_u64 v[0:1], v[0:1], 0, s[12:13]
	s_mov_b32 m0, s62
	s_add_u32 s4, s40, 0x40080
	global_load_lds_dwordx4 v[0:1], off
	v_lshl_add_u64 v[0:1], v[2:3], 0, s[12:13]
	s_mov_b32 m0, s63
	s_addc_u32 s5, s41, 0
	global_load_lds_dwordx4 v[0:1], off
	s_add_i32 m0, s27, 0x1c000
	v_lshl_add_u64 v[0:1], s[4:5], 0, v[170:171]
	global_load_lds_dwordx4 v[0:1], off
	v_lshl_add_u64 v[0:1], s[4:5], 0, v[174:175]
	s_add_i32 m0, s27, 0x1e000
	s_cmpk_lt_u32 s14, 0x100
	global_load_lds_dwordx4 v[0:1], off
	v_bfe_u32 v0, v8, 4, 2
	v_and_b32_e32 v1, 15, v8
	v_lshlrev_b32_e32 v2, 4, v0
	v_lshl_or_b32 v177, s2, 6, v1
	v_lshl_or_b32 v1, v1, 6, v2
	v_lshlrev_b32_e32 v2, 2, v8
	v_and_b32_e32 v2, 32, v2
	v_bitop3_b32 v206, v1, s3, v2 bitop3:0xde
	v_cmp_eq_u32_e64 s[2:3], 0, v0
	v_lshl_or_b32 v207, v0, 3, s16
	v_lshlrev_b32_e32 v0, 14, v9
	v_and_b32_e32 v0, 0xffff8000, v0
	v_bitop3_b32 v3, v1, s15, v2 bitop3:0xde
	v_lshl_add_u32 v0, v10, 11, v0
	v_and_b32_e32 v1, 1, v9
	v_lshl_or_b32 v0, v1, 6, v0
	v_lshl_add_u32 v178, v11, 1, v0
	v_lshlrev_b32_e32 v0, 14, v12
	v_and_b32_e32 v0, 0xffff8000, v0
	v_lshl_add_u32 v0, v13, 11, v0
	v_and_b32_e32 v1, 1, v12
	s_waitcnt vmcnt(8)
	s_barrier
	s_waitcnt vmcnt(6)
	v_lshl_or_b32 v0, v1, 6, v0
	s_cselect_b64 s[14:15], -1, 0
	v_lshl_add_u32 v180, v14, 1, v0
	s_add_i32 s66, 0, 0x10000
	s_add_i32 s67, 0, 0x14000
	v_mbcnt_lo_u32_b32 v0, -1, 0
	s_ashr_i32 s64, s9, 31
	s_ashr_i32 s65, s8, 31
	v_mov_b32_e32 v179, v171
	v_mov_b32_e32 v181, v171
	v_mov_b64_e32 v[182:183], 0x200
	v_mov_b64_e32 v[184:185], 0x1ff
	v_add_u32_e32 v208, s66, v206
	v_add_u32_e32 v209, s67, v206
	v_add_u32_e32 v210, 0, v3
	v_mbcnt_hi_u32_b32 v211, -1, v0
	s_barrier
	s_branch .LBB0_727

.Lold_4:
	s_add_u32 s6, s30, 0x181000
	s_addc_u32 s7, s31, 0
	s_add_u32 s49, s30, 0x13921000
	s_addc_u32 s54, s31, 0
	s_lshl_b32 s10, s10, 5
	s_and_b32 s16, s10, 0x60
	s_mov_b64 s[10:11], 0x80
	s_add_i32 m0, s23, 0x18000
	v_lshl_add_u64 v[6:7], v[6:7], 0, s[10:11]
	s_lshl_b32 s13, s3, 13
	s_lshl_b32 s17, s16, 7
	global_load_lds_dwordx4 v[6:7], off
	v_lshl_add_u64 v[4:5], v[4:5], 0, s[10:11]
	s_add_i32 m0, s23, 0x1a000
	s_add_i32 s55, s23, 0x8000
	s_add_i32 s56, s23, 0xa000
	global_load_lds_dwordx4 v[4:5], off
	v_lshl_add_u64 v[0:1], v[0:1], 0, s[10:11]
	s_mov_b32 m0, s55
	s_add_u32 s14, s26, 0x40080
	global_load_lds_dwordx4 v[0:1], off
	v_lshl_add_u64 v[0:1], v[2:3], 0, s[10:11]
	s_mov_b32 m0, s56
	s_addc_u32 s15, s27, 0
	global_load_lds_dwordx4 v[0:1], off
	s_add_i32 m0, s23, 0x1c000
	v_lshl_add_u64 v[0:1], s[14:15], 0, v[146:147]
	global_load_lds_dwordx4 v[0:1], off
	v_lshl_add_u64 v[0:1], s[14:15], 0, v[150:151]
	s_add_i32 m0, s23, 0x1e000
	v_and_b32_e32 v2, 15, v8
	global_load_lds_dwordx4 v[0:1], off
	v_bfe_u32 v1, v8, 4, 2
	v_lshlrev_b32_e32 v0, 3, v1
	v_lshlrev_b32_e32 v1, 4, v1
	v_lshl_or_b32 v168, s3, 6, v2
	v_lshl_or_b32 v1, v2, 6, v1
	v_lshlrev_b32_e32 v2, 2, v8
	v_and_b32_e32 v2, 32, v2
	v_bitop3_b32 v3, v1, s13, v2 bitop3:0xde
	v_bitop3_b32 v169, v1, s17, v2 bitop3:0xde
	v_lshlrev_b32_e32 v1, 14, v9
	v_and_b32_e32 v1, 0xffff8000, v1
	v_lshl_add_u32 v1, v10, 11, v1
	v_and_b32_e32 v2, 1, v9
	v_lshl_or_b32 v1, v2, 6, v1
	v_lshl_add_u32 v152, v11, 1, v1
	v_lshlrev_b32_e32 v1, 14, v12
	v_and_b32_e32 v1, 0xffff8000, v1
	s_waitcnt vmcnt(8)
	s_barrier
	s_waitcnt vmcnt(6)
	s_cmpk_lt_u32 s12, 0x100
	v_lshl_add_u32 v1, v13, 11, v1
	v_and_b32_e32 v2, 1, v12
	s_cselect_b64 s[12:13], -1, 0
	v_lshl_or_b32 v1, v2, 6, v1
	s_add_i32 s58, 0, 0x10000
	s_add_i32 s59, 0, 0x14000
	s_sext_i32_i16 s62, s2
	s_ashr_i32 s57, s9, 31
	v_or_b32_e32 v170, s16, v0
	v_mov_b32_e32 v153, v147
	v_lshl_add_u32 v154, v14, 1, v1
	v_mov_b32_e32 v155, v147
	v_mov_b64_e32 v[156:157], 0x5ac
	v_mov_b64_e32 v[158:159], 0x5ab
	v_add_u32_e32 v171, s58, v169
	v_add_u32_e32 v172, s59, v169
	v_add_u32_e32 v173, 0, v3
	s_movk_i32 s60, 0x1600
	s_lshl_b32 s61, s16, 2
	v_lshlrev_b32_e32 v174, 2, v0
	v_mov_b32_e32 v175, 0x358637bd
	s_barrier
	s_branch .LBB0_866

.Lold_5:
	s_add_u32 s47, s30, 0x8000
	s_addc_u32 s48, s31, 0
	s_add_u32 s49, s30, 0x1cc000
	s_addc_u32 s54, s31, 0
	s_add_u32 s12, s30, 0x191800
	s_addc_u32 s13, s31, 0
	s_lshl_b32 s2, s2, 5
	s_mov_b64 s[16:17], 0x80
	s_and_b32 s26, s2, 0x60
	s_add_i32 m0, s40, 0x18000
	v_lshl_add_u64 v[6:7], v[6:7], 0, s[16:17]
	s_lshl_b32 s5, s0, 13
	s_lshl_b32 s18, s26, 7
	global_load_lds_dwordx4 v[6:7], off
	v_lshl_add_u64 v[4:5], v[4:5], 0, s[16:17]
	s_add_i32 m0, s40, 0x1a000
	s_add_i32 s55, s40, 0x8000
	s_add_i32 s56, s40, 0xa000
	global_load_lds_dwordx4 v[4:5], off
	v_lshl_add_u64 v[0:1], v[0:1], 0, s[16:17]
	s_mov_b32 m0, s55
	s_add_u32 s2, s24, 0xb0080
	global_load_lds_dwordx4 v[0:1], off
	v_lshl_add_u64 v[0:1], v[2:3], 0, s[16:17]
	s_mov_b32 m0, s56
	s_addc_u32 s3, s25, 0
	global_load_lds_dwordx4 v[0:1], off
	s_add_i32 m0, s40, 0x1c000
	v_lshl_add_u64 v[0:1], s[2:3], 0, v[162:163]
	global_load_lds_dwordx4 v[0:1], off
	v_lshl_add_u64 v[0:1], s[2:3], 0, v[166:167]
	s_add_i32 m0, s40, 0x1e000
	s_cmpk_lt_u32 s4, 0x100
	global_load_lds_dwordx4 v[0:1], off
	v_bfe_u32 v0, v8, 4, 2
	v_and_b32_e32 v1, 15, v8
	v_lshlrev_b32_e32 v2, 4, v0
	v_lshl_or_b32 v177, s0, 6, v1
	v_lshl_or_b32 v1, v1, 6, v2
	v_lshlrev_b32_e32 v2, 2, v8
	v_and_b32_e32 v2, 32, v2
	v_bitop3_b32 v3, v1, s5, v2 bitop3:0xde
	v_bitop3_b32 v206, v1, s18, v2 bitop3:0xde
	v_cmp_eq_u32_e64 s[2:3], 0, v0
	v_lshl_or_b32 v207, v0, 3, s26
	v_lshrrev_b32_e32 v1, 1, v9
	v_mul_lo_u32 v0, v11, s1
	s_mov_b32 s0, 0xb000
	v_mad_u64_u32 v[0:1], s[4:5], v1, s0, v[0:1]
	v_or_b32_e32 v0, v0, v10
	s_mov_b64 s[20:21], 0xb0080
	v_add_lshl_u32 v0, v0, v12, 1
	v_mov_b32_e32 v1, v163
	v_lshl_add_u64 v[168:169], v[0:1], 0, s[20:21]
	v_lshrrev_b32_e32 v1, 1, v13
	v_mul_lo_u32 v0, v14, s1
	v_mad_u64_u32 v[0:1], s[0:1], v1, s0, v[0:1]
	v_or_b32_e32 v0, v0, v15
	s_waitcnt vmcnt(8)
	s_barrier
	s_waitcnt vmcnt(6)
	v_add_lshl_u32 v0, v0, v16, 1
	v_mov_b32_e32 v1, v163
	s_cselect_b64 s[18:19], -1, 0
	v_lshl_add_u64 v[170:171], v[0:1], 0, s[20:21]
	s_add_i32 s59, 0, 0x10000
	s_add_i32 s60, 0, 0x14000
	v_mbcnt_lo_u32_b32 v0, -1, 0
	s_ashr_i32 s57, s9, 31
	s_ashr_i32 s58, s8, 31
	v_mov_b64_e32 v[172:173], 0x100
	v_mov_b64_e32 v[174:175], 0xff
	v_add_u32_e32 v208, s59, v206
	v_add_u32_e32 v209, s60, v206
	v_add_u32_e32 v210, 0, v3
	v_mbcnt_hi_u32_b32 v211, -1, v0
	s_barrier
	s_branch .LBB0_983

.Lold_6:
	s_add_u32 s6, s30, 0x191800
	s_addc_u32 s7, s31, 0
	s_add_u32 s49, s30, 0x13931800
	s_addc_u32 s54, s31, 0
	s_lshl_b32 s10, s10, 5
	s_and_b32 s16, s10, 0x60
	s_mov_b64 s[10:11], 0x80
	s_add_i32 m0, s23, 0x18000
	v_lshl_add_u64 v[6:7], v[6:7], 0, s[10:11]
	s_lshl_b32 s13, s3, 13
	s_lshl_b32 s17, s16, 7
	global_load_lds_dwordx4 v[6:7], off
	v_lshl_add_u64 v[4:5], v[4:5], 0, s[10:11]
	s_add_i32 m0, s23, 0x1a000
	s_add_i32 s55, s23, 0x8000
	s_add_i32 s56, s23, 0xa000
	global_load_lds_dwordx4 v[4:5], off
	v_lshl_add_u64 v[0:1], v[0:1], 0, s[10:11]
	s_mov_b32 m0, s55
	s_add_u32 s14, s26, 0x40080
	global_load_lds_dwordx4 v[0:1], off
	v_lshl_add_u64 v[0:1], v[2:3], 0, s[10:11]
	s_mov_b32 m0, s56
	s_addc_u32 s15, s27, 0
	global_load_lds_dwordx4 v[0:1], off
	s_add_i32 m0, s23, 0x1c000
	v_lshl_add_u64 v[0:1], s[14:15], 0, v[146:147]
	global_load_lds_dwordx4 v[0:1], off
	v_lshl_add_u64 v[0:1], s[14:15], 0, v[150:151]
	s_add_i32 m0, s23, 0x1e000
	v_and_b32_e32 v2, 15, v8
	global_load_lds_dwordx4 v[0:1], off
	v_bfe_u32 v1, v8, 4, 2
	v_lshlrev_b32_e32 v0, 3, v1
	v_lshlrev_b32_e32 v1, 4, v1
	v_lshl_or_b32 v168, s3, 6, v2
	v_lshl_or_b32 v1, v2, 6, v1
	v_lshlrev_b32_e32 v2, 2, v8
	v_and_b32_e32 v2, 32, v2
	v_bitop3_b32 v3, v1, s13, v2 bitop3:0xde
	v_bitop3_b32 v169, v1, s17, v2 bitop3:0xde
	v_lshlrev_b32_e32 v1, 14, v9
	v_and_b32_e32 v1, 0xffff8000, v1
	v_lshl_add_u32 v1, v10, 11, v1
	v_and_b32_e32 v2, 1, v9
	v_lshl_or_b32 v1, v2, 6, v1
	v_lshl_add_u32 v152, v11, 1, v1
	v_lshlrev_b32_e32 v1, 14, v12
	v_and_b32_e32 v1, 0xffff8000, v1
	s_waitcnt vmcnt(8)
	s_barrier
	s_waitcnt vmcnt(6)
	s_cmpk_lt_u32 s12, 0x100
	v_lshl_add_u32 v1, v13, 11, v1
	v_and_b32_e32 v2, 1, v12
	s_cselect_b64 s[12:13], -1, 0
	v_lshl_or_b32 v1, v2, 6, v1
	s_add_i32 s58, 0, 0x10000
	s_add_i32 s59, 0, 0x14000
	s_sext_i32_i16 s62, s2
	s_ashr_i32 s57, s9, 31
	v_or_b32_e32 v170, s16, v0
	v_mov_b32_e32 v153, v147
	v_lshl_add_u32 v154, v14, 1, v1
	v_mov_b32_e32 v155, v147
	v_mov_b64_e32 v[156:157], 0x5ac
	v_mov_b64_e32 v[158:159], 0x5ab
	v_add_u32_e32 v171, s58, v169
	v_add_u32_e32 v172, s59, v169
	v_add_u32_e32 v173, 0, v3
	s_movk_i32 s60, 0x1600
	s_lshl_b32 s61, s16, 2
	v_lshlrev_b32_e32 v174, 2, v0
	v_mov_b32_e32 v175, 0x358637bd
	s_barrier
	s_branch .LBB0_1110

.Lold_7:
	s_add_u32 s47, s30, 0x1d000
	s_addc_u32 s48, s31, 0
	s_add_u32 s49, s30, 0x1cf000
	s_addc_u32 s50, s31, 0
	s_add_u32 s12, s30, 0x1a2000
	s_addc_u32 s13, s31, 0
	s_lshl_b32 s2, s2, 5
	s_mov_b64 s[16:17], 0x80
	s_and_b32 s26, s2, 0x60
	s_add_i32 m0, s40, 0x18000
	v_lshl_add_u64 v[6:7], v[6:7], 0, s[16:17]
	s_lshl_b32 s5, s0, 13
	s_lshl_b32 s18, s26, 7
	global_load_lds_dwordx4 v[6:7], off
	v_lshl_add_u64 v[4:5], v[4:5], 0, s[16:17]
	s_add_i32 m0, s40, 0x1a000
	s_add_i32 s51, s40, 0x8000
	s_add_i32 s52, s40, 0xa000
	global_load_lds_dwordx4 v[4:5], off
	v_lshl_add_u64 v[0:1], v[0:1], 0, s[16:17]
	s_mov_b32 m0, s51
	s_add_u32 s2, s24, 0xb0080
	global_load_lds_dwordx4 v[0:1], off
	v_lshl_add_u64 v[0:1], v[2:3], 0, s[16:17]
	s_mov_b32 m0, s52
	s_addc_u32 s3, s25, 0
	global_load_lds_dwordx4 v[0:1], off
	s_add_i32 m0, s40, 0x1c000
	v_lshl_add_u64 v[0:1], s[2:3], 0, v[162:163]
	global_load_lds_dwordx4 v[0:1], off
	v_lshl_add_u64 v[0:1], s[2:3], 0, v[166:167]
	s_add_i32 m0, s40, 0x1e000
	s_cmpk_lt_u32 s4, 0x100
	global_load_lds_dwordx4 v[0:1], off
	v_bfe_u32 v0, v8, 4, 2
	v_and_b32_e32 v1, 15, v8
	v_lshlrev_b32_e32 v2, 4, v0
	v_lshl_or_b32 v177, s0, 6, v1
	v_lshl_or_b32 v1, v1, 6, v2
	v_lshlrev_b32_e32 v2, 2, v8
	v_and_b32_e32 v2, 32, v2
	v_bitop3_b32 v3, v1, s5, v2 bitop3:0xde
	v_bitop3_b32 v206, v1, s18, v2 bitop3:0xde
	v_cmp_eq_u32_e64 s[2:3], 0, v0
	v_lshl_or_b32 v207, v0, 3, s26
	v_lshrrev_b32_e32 v1, 1, v9
	v_mul_lo_u32 v0, v11, s1
	s_mov_b32 s0, 0xb000
	v_mad_u64_u32 v[0:1], s[4:5], v1, s0, v[0:1]
	v_or_b32_e32 v0, v0, v10
	s_mov_b64 s[20:21], 0xb0080
	v_add_lshl_u32 v0, v0, v12, 1
	v_mov_b32_e32 v1, v163
	v_lshl_add_u64 v[168:169], v[0:1], 0, s[20:21]
	v_lshrrev_b32_e32 v1, 1, v13
	v_mul_lo_u32 v0, v14, s1
	v_mad_u64_u32 v[0:1], s[0:1], v1, s0, v[0:1]
	v_or_b32_e32 v0, v0, v15
	s_waitcnt vmcnt(8)
	s_barrier
	s_waitcnt vmcnt(6)
	v_add_lshl_u32 v0, v0, v16, 1
	v_mov_b32_e32 v1, v163
	s_cselect_b64 s[18:19], -1, 0
	v_lshl_add_u64 v[170:171], v[0:1], 0, s[20:21]
	s_add_i32 s55, 0, 0x10000
	s_add_i32 s56, 0, 0x14000
	v_mbcnt_lo_u32_b32 v0, -1, 0
	s_ashr_i32 s53, s9, 31
	s_ashr_i32 s54, s8, 31
	v_mov_b64_e32 v[172:173], 0x100
	v_mov_b64_e32 v[174:175], 0xff
	v_add_u32_e32 v208, s55, v206
	v_add_u32_e32 v209, s56, v206
	v_add_u32_e32 v210, 0, v3
	v_mbcnt_hi_u32_b32 v211, -1, v0
	s_barrier
	s_branch .LBB0_1209

.Lold_8:
	s_add_u32 s59, s30, 0x13942000
	s_addc_u32 s60, s31, 0
	s_lshl_b32 s1, s12, 5
	s_mov_b64 s[12:13], 0x80
	s_and_b32 s18, s1, 0x60
	s_add_i32 m0, s54, 0x18000
	v_lshl_add_u64 v[6:7], v[6:7], 0, s[12:13]
	s_lshl_b32 s15, s14, 13
	s_lshl_b32 s19, s18, 7
	global_load_lds_dwordx4 v[6:7], off
	v_lshl_add_u64 v[2:3], v[2:3], 0, s[12:13]
	s_add_i32 m0, s54, 0x1a000
	s_add_i32 s61, s54, 0x8000
	s_add_i32 s62, s54, 0xa000
	global_load_lds_dwordx4 v[2:3], off
	v_lshl_add_u64 v[0:1], v[0:1], 0, s[12:13]
	s_mov_b32 m0, s61
	s_add_u32 s16, s48, 0x40080
	global_load_lds_dwordx4 v[0:1], off
	v_lshl_add_u64 v[0:1], v[4:5], 0, s[12:13]
	s_mov_b32 m0, s62
	s_addc_u32 s17, s49, 0
	global_load_lds_dwordx4 v[0:1], off
	s_add_i32 m0, s54, 0x1c000
	v_lshl_add_u64 v[0:1], s[16:17], 0, v[148:149]
	global_load_lds_dwordx4 v[0:1], off
	v_lshl_add_u64 v[0:1], s[16:17], 0, v[144:145]
	s_add_i32 m0, s54, 0x1e000
	v_and_b32_e32 v2, 15, v10
	global_load_lds_dwordx4 v[0:1], off
	v_bfe_u32 v1, v10, 4, 2
	v_lshlrev_b32_e32 v0, 3, v1
	v_lshlrev_b32_e32 v1, 4, v1
	v_lshl_or_b32 v164, s14, 6, v2
	v_lshl_or_b32 v1, v2, 6, v1
	v_lshlrev_b32_e32 v2, 2, v10
	v_and_b32_e32 v2, 32, v2
	v_bitop3_b32 v3, v1, s15, v2 bitop3:0xde
	v_bitop3_b32 v165, v1, s19, v2 bitop3:0xde
	v_lshlrev_b32_e32 v1, 14, v13
	v_and_b32_e32 v1, 0xffff8000, v1
	v_lshl_add_u32 v1, v12, 11, v1
	v_and_b32_e32 v2, 1, v13
	v_lshl_or_b32 v1, v2, 6, v1
	v_lshl_add_u32 v152, v14, 1, v1
	v_lshlrev_b32_e32 v1, 14, v8
	v_and_b32_e32 v1, 0xffff8000, v1
	s_waitcnt vmcnt(8)
	s_barrier
	s_waitcnt vmcnt(6)
	s_cmpk_lt_u32 s3, 0x100
	v_lshl_add_u32 v1, v9, 11, v1
	v_and_b32_e32 v2, 1, v8
	s_cselect_b64 s[14:15], -1, 0
	v_lshl_or_b32 v1, v2, 6, v1
	s_add_i32 s64, 0, 0x10000
	s_add_i32 s65, 0, 0x14000
	s_sext_i32_i8 s1, s2
	s_ashr_i32 s63, s9, 31
	v_or_b32_e32 v166, s18, v0
	v_mov_b32_e32 v153, v149
	v_lshl_add_u32 v154, v11, 1, v1
	v_mov_b32_e32 v155, v149
	v_mov_b64_e32 v[156:157], 0x300
	v_mov_b64_e32 v[158:159], 0x2ff
	v_add_u32_e32 v167, s64, v165
	v_add_u32_e32 v168, s65, v165
	v_add_u32_e32 v169, 0, v3
	s_movk_i32 s66, 0x1600
	s_lshl_b32 s67, s18, 2
	v_lshlrev_b32_e32 v170, 2, v0
	v_mov_b32_e32 v171, 0x358637bd
	s_mov_b32 s68, 0x40000
	s_mov_b64 s[16:17], 0x48000
	s_mov_b32 s69, 0x48000
	s_mov_b64 s[18:19], 0x50000
	s_mov_b32 s70, 0x50000
	s_mov_b64 s[24:25], 0x58000
	s_mov_b32 s71, 0x58000
	s_barrier
	s_branch .LBB0_1330

.Lold_9:
	s_add_u32 s52, s30, 0x20000
	s_addc_u32 s53, s31, 0
	s_add_u32 s54, s30, 0x1d2000
	s_addc_u32 s55, s31, 0
	s_add_u32 s10, s30, 0x1b2800
	s_addc_u32 s11, s31, 0
	s_lshl_b32 s3, s3, 5
	s_mov_b64 s[12:13], 0x80
	s_and_b32 s16, s3, 0x60
	s_add_i32 m0, s27, 0x18000
	v_lshl_add_u64 v[6:7], v[6:7], 0, s[12:13]
	s_lshl_b32 s15, s2, 13
	s_lshl_b32 s3, s16, 7
	global_load_lds_dwordx4 v[6:7], off
	v_lshl_add_u64 v[4:5], v[4:5], 0, s[12:13]
	s_add_i32 m0, s27, 0x1a000
	s_add_i32 s56, s27, 0x8000
	s_add_i32 s57, s27, 0xa000
	global_load_lds_dwordx4 v[4:5], off
	v_lshl_add_u64 v[0:1], v[0:1], 0, s[12:13]
	s_mov_b32 m0, s56
	s_add_u32 s4, s40, 0x40080
	global_load_lds_dwordx4 v[0:1], off
	v_lshl_add_u64 v[0:1], v[2:3], 0, s[12:13]
	s_mov_b32 m0, s57
	s_addc_u32 s5, s41, 0
	global_load_lds_dwordx4 v[0:1], off
	s_add_i32 m0, s27, 0x1c000
	v_lshl_add_u64 v[0:1], s[4:5], 0, v[180:181]
	global_load_lds_dwordx4 v[0:1], off
	v_lshl_add_u64 v[0:1], s[4:5], 0, v[184:185]
	s_add_i32 m0, s27, 0x1e000
	s_cmpk_lt_u32 s14, 0x100
	global_load_lds_dwordx4 v[0:1], off
	v_bfe_u32 v0, v8, 4, 2
	v_and_b32_e32 v1, 15, v8
	v_lshlrev_b32_e32 v2, 4, v0
	v_lshl_or_b32 v177, s2, 6, v1
	v_lshl_or_b32 v1, v1, 6, v2
	v_lshlrev_b32_e32 v2, 2, v8
	v_and_b32_e32 v2, 32, v2
	v_bitop3_b32 v206, v1, s3, v2 bitop3:0xde
	v_cmp_eq_u32_e64 s[2:3], 0, v0
	v_lshl_or_b32 v207, v0, 3, s16
	v_lshlrev_b32_e32 v0, 14, v9
	v_and_b32_e32 v0, 0xffff8000, v0
	v_bitop3_b32 v3, v1, s15, v2 bitop3:0xde
	v_lshl_add_u32 v0, v10, 11, v0
	v_and_b32_e32 v1, 1, v9
	v_lshl_or_b32 v0, v1, 6, v0
	v_lshl_add_u32 v186, v11, 1, v0
	v_lshlrev_b32_e32 v0, 14, v12
	v_and_b32_e32 v0, 0xffff8000, v0
	v_lshl_add_u32 v0, v13, 11, v0
	v_and_b32_e32 v1, 1, v12
	s_waitcnt vmcnt(8)
	s_barrier
	s_waitcnt vmcnt(6)
	v_lshl_or_b32 v0, v1, 6, v0
	s_cselect_b64 s[14:15], -1, 0
	v_lshl_add_u32 v188, v14, 1, v0
	s_add_i32 s60, 0, 0x10000
	s_add_i32 s61, 0, 0x14000
	v_mbcnt_lo_u32_b32 v0, -1, 0
	s_ashr_i32 s58, s9, 31
	s_ashr_i32 s59, s8, 31
	v_mov_b32_e32 v187, v181
	v_mov_b32_e32 v189, v181
	v_mov_b64_e32 v[190:191], 0x100
	v_mov_b64_e32 v[192:193], 0xff
	v_add_u32_e32 v208, s60, v206
	v_add_u32_e32 v209, s61, v206
	v_add_u32_e32 v210, 0, v3
	v_mbcnt_hi_u32_b32 v211, -1, v0
	s_barrier
	s_branch .LBB0_1491

.Lold_10:
	s_add_u32 s6, s30, 0x1b2800
	s_addc_u32 s7, s31, 0
	s_add_u32 s50, s30, 0x13952800
	s_addc_u32 s51, s31, 0
	s_lshl_b32 s10, s10, 5
	s_and_b32 s16, s10, 0x60
	s_mov_b64 s[10:11], 0x80
	s_add_i32 m0, s23, 0x18000
	v_lshl_add_u64 v[6:7], v[6:7], 0, s[10:11]
	s_lshl_b32 s13, s12, 13
	s_lshl_b32 s17, s16, 7
	global_load_lds_dwordx4 v[6:7], off
	v_lshl_add_u64 v[4:5], v[4:5], 0, s[10:11]
	s_add_i32 m0, s23, 0x1a000
	s_add_i32 s52, s23, 0x8000
	s_add_i32 s53, s23, 0xa000
	global_load_lds_dwordx4 v[4:5], off
	v_lshl_add_u64 v[0:1], v[0:1], 0, s[10:11]
	s_mov_b32 m0, s52
	s_add_u32 s14, s26, 0x40080
	global_load_lds_dwordx4 v[0:1], off
	v_lshl_add_u64 v[0:1], v[2:3], 0, s[10:11]
	s_mov_b32 m0, s53
	s_addc_u32 s15, s27, 0
	global_load_lds_dwordx4 v[0:1], off
	s_add_i32 m0, s23, 0x1c000
	v_lshl_add_u64 v[0:1], s[14:15], 0, v[148:149]
	global_load_lds_dwordx4 v[0:1], off
	v_lshl_add_u64 v[0:1], s[14:15], 0, v[144:145]
	s_add_i32 m0, s23, 0x1e000
	v_and_b32_e32 v2, 15, v10
	global_load_lds_dwordx4 v[0:1], off
	v_bfe_u32 v1, v10, 4, 2
	v_lshlrev_b32_e32 v0, 3, v1
	v_lshlrev_b32_e32 v1, 4, v1
	v_lshl_or_b32 v168, s12, 6, v2
	v_lshl_or_b32 v1, v2, 6, v1
	v_lshlrev_b32_e32 v2, 2, v10
	v_and_b32_e32 v2, 32, v2
	v_bitop3_b32 v3, v1, s13, v2 bitop3:0xde
	v_bitop3_b32 v169, v1, s17, v2 bitop3:0xde
	v_lshlrev_b32_e32 v1, 14, v13
	v_and_b32_e32 v1, 0xffff8000, v1
	v_lshl_add_u32 v1, v12, 11, v1
	v_and_b32_e32 v2, 1, v13
	v_lshl_or_b32 v1, v2, 6, v1
	v_lshl_add_u32 v152, v14, 1, v1
	v_lshlrev_b32_e32 v1, 14, v8
	v_and_b32_e32 v1, 0xffff8000, v1
	s_waitcnt vmcnt(8)
	s_barrier
	s_waitcnt vmcnt(6)
	s_cmpk_lt_u32 s3, 0x100
	v_lshl_add_u32 v1, v9, 11, v1
	v_and_b32_e32 v2, 1, v8
	s_cselect_b64 s[12:13], -1, 0
	v_lshl_or_b32 v1, v2, 6, v1
	s_add_i32 s55, 0, 0x10000
	s_add_i32 s56, 0, 0x14000
	s_sext_i32_i16 s59, s2
	s_ashr_i32 s54, s9, 31
	v_or_b32_e32 v170, s16, v0
	v_mov_b32_e32 v153, v149
	v_lshl_add_u32 v154, v11, 1, v1
	v_mov_b32_e32 v155, v149
	v_mov_b64_e32 v[156:157], 0x580
	v_mov_b64_e32 v[158:159], 0x57f
	v_add_u32_e32 v171, s55, v169
	v_add_u32_e32 v172, s56, v169
	v_add_u32_e32 v173, 0, v3
	s_movk_i32 s57, 0x1600
	s_lshl_b32 s58, s16, 2
	v_lshlrev_b32_e32 v174, 2, v0
	v_mov_b32_e32 v175, 0x358637bd
	s_barrier
	s_branch .LBB0_1582

.Lold_11:
	s_add_u32 s46, s30, 0x23000
	s_addc_u32 s47, s31, 0
	s_lshl_b32 s10, s10, 5
	s_and_b32 s16, s10, 0x60
	s_mov_b64 s[10:11], 0x80
	s_add_i32 m0, s41, 0x18000
	v_lshl_add_u64 v[6:7], v[6:7], 0, s[10:11]
	s_lshl_b32 s14, s0, 13
	s_lshl_b32 s15, s16, 7
	global_load_lds_dwordx4 v[6:7], off
	v_lshl_add_u64 v[2:3], v[2:3], 0, s[10:11]
	s_add_i32 m0, s41, 0x1a000
	s_add_i32 s48, s41, 0x8000
	s_add_i32 s49, s41, 0xa000
	global_load_lds_dwordx4 v[2:3], off
	v_lshl_add_u64 v[0:1], v[0:1], 0, s[10:11]
	s_mov_b32 m0, s48
	s_add_u32 s12, s24, 0xb0080
	global_load_lds_dwordx4 v[0:1], off
	v_lshl_add_u64 v[0:1], v[4:5], 0, s[10:11]
	s_mov_b32 m0, s49
	s_addc_u32 s13, s25, 0
	global_load_lds_dwordx4 v[0:1], off
	s_add_i32 m0, s41, 0x1c000
	v_lshl_add_u64 v[0:1], s[12:13], 0, v[130:131]
	global_load_lds_dwordx4 v[0:1], off
	v_lshl_add_u64 v[0:1], s[12:13], 0, v[134:135]
	s_add_i32 m0, s41, 0x1e000
	s_sext_i32_i8 s57, s3
	global_load_lds_dwordx4 v[0:1], off
	v_bfe_u32 v0, v204, 4, 2
	v_and_b32_e32 v1, 15, v204
	v_lshlrev_b32_e32 v2, 4, v0
	v_lshl_or_b32 v166, s0, 6, v1
	v_lshl_or_b32 v1, v1, 6, v2
	v_lshlrev_b32_e32 v2, 2, v204
	v_and_b32_e32 v2, 32, v2
	v_bitop3_b32 v3, v1, s14, v2 bitop3:0xde
	v_bitop3_b32 v167, v1, s15, v2 bitop3:0xde
	v_lshl_or_b32 v168, v0, 3, s16
	v_lshrrev_b32_e32 v1, 1, v8
	v_mul_lo_u32 v0, v10, s1
	s_mov_b32 s0, 0xb000
	s_cmpk_lt_u32 s2, 0x100
	v_mad_u64_u32 v[0:1], s[2:3], v1, s0, v[0:1]
	v_or_b32_e32 v0, v0, v9
	s_mov_b64 s[14:15], 0xb0080
	v_add_lshl_u32 v0, v0, v11, 1
	v_mov_b32_e32 v1, v131
	v_lshl_add_u64 v[136:137], v[0:1], 0, s[14:15]
	v_lshrrev_b32_e32 v1, 1, v12
	v_mul_lo_u32 v0, v13, s1
	v_mad_u64_u32 v[0:1], s[0:1], v1, s0, v[0:1]
	s_waitcnt vmcnt(8)
	s_barrier
	s_waitcnt vmcnt(6)
	v_or_b32_e32 v0, v0, v14
	s_cselect_b64 s[12:13], -1, 0
	v_add_lshl_u32 v0, v0, v15, 1
	v_mov_b32_e32 v1, v131
	s_add_i32 s51, 0, 0x10000
	s_add_i32 s52, 0, 0x14000
	s_ashr_i32 s50, s9, 31
	v_lshl_add_u64 v[138:139], v[0:1], 0, s[14:15]
	v_mov_b64_e32 v[140:141], 0x100
	v_mov_b64_e32 v[142:143], 0xff
	v_add_u32_e32 v169, s51, v167
	v_add_u32_e32 v170, s52, v167
	v_add_u32_e32 v171, 0, v3
	s_movk_i32 s53, 0x2400
	s_mov_b64 s[14:15], 0x80000
	s_mov_b64 s[16:17], 0x90000
	s_mov_b64 s[18:19], 0xa0000
	s_barrier
	s_branch .LBB0_1657
